# loader waves: block-diagonal A operands for the two LoRA matmuls, one accumulator chain per channel tile, the 16 per-lane selects removed
# speedup vs baseline: 1.0037x; 1.0037x over previous
; __device__ __forceinline__ void phase_scan(const Params& p, LAS unsigned char* lds) {
;     ...
;         const int pw_ = wave & 3, s_sub = lane >> 3, c8 = (lane & 7) * 8, s_l = 8 * pw_ + s_sub;
;         h16x8 mu_r8, mu_k8, mu_v8, mu_w8, mu_a8; f32x2 w0r[4], a0r[4], kkr[4], kar[4], omk[4], rkr[4];
; #pragma unroll
;         for (int e = 0; e < 8; ++e) { mu_r8[e] = (h16)mu[64 * h + c8 + e]; mu_k8[e] = (h16)mu[1024 + 64 * h + c8 + e]; mu_v8[e] = (h16)mu[2048 + 64 * h + c8 + e]; mu_w8[e] = (h16)mu[3072 + c8 + e]; mu_a8[e] = (h16)mu[3136 + c8 + e];
;             w0r[e >> 1][e & 1] = w0[c8 + e]; a0r[e >> 1][e & 1] = a0[c8 + e]; kkr[e >> 1][e & 1] = kkw[c8 + e]; kar[e >> 1][e & 1] = kaw[c8 + e]; omk[e >> 1][e & 1] = 1.f - kaw[c8 + e]; rkr[e >> 1][e & 1] = rkw[c8 + e]; }
;         f32x2 S01 = {0.f, 0.f}, S23 = {0.f, 0.f};
;         const int srow = 4 * (wave & 3) + (lane >> 4), j0 = 4 * (lane & 15);
;         const h16x8 z8 = {0, 0, 0, 0, 0, 0, 0, 0};
;         h16x8 pr, pk, pv, pw, pa, qr_, qk_, qv_, qw_, qa_;
;         const h16 *pcA, *pcB, *ppA, *ppB;
;         { const int t0_ = dir ? (SEQ - 1 - s_l) : s_l; pcA = PC + (size_t)(b * SEQ + t0_) * 3200 + c8 + 64 * h; pcB = pcA + 2048 - 64 * h;
;           const long po_ = (s_l > 0) ? (dir ? 3200 : -3200) : 0; ppA = pcA + po_; ppB = pcB + po_; }
;         const long cstride_ = dir ? -32 * 3200 : 32 * 3200;
;     ...
;         if (wave >= 4) { SCAN_LOAD_RAW(); if (s_l == 0) { qr_ = z8; qk_ = z8; qv_ = z8; qw_ = z8; qa_ = z8; } }
;         __syncthreads();
.LBB0_601:
	s_or_b64 exec, exec, s[10:11]
	s_waitcnt vmcnt(16)
	v_cvt_f16_f32_e32 v64, v64
	s_waitcnt vmcnt(13)
	v_cvt_f16_f32_e32 v68, v94
	v_cvt_f16_f32_e32 v0, v60
	s_waitcnt vmcnt(11)
	v_cvt_f16_f32_e32 v69, v98
	v_cvt_f16_f32_e32 v3, v90
	v_cvt_pk_f16_f32 v65, v65, v66
	v_cvt_pk_f16_f32 v90, v95, v96
	v_cvt_pk_f16_f32 v61, v61, v62
	v_pack_b32_f16 v62, v64, v65
	v_pack_b32_f16 v64, v68, v90
	v_cvt_pk_f16_f32 v68, v99, v100
	s_lshl_b64 s[48:49], s[12:13], 25
	s_lshl_b64 s[10:11], s[12:13], 20
	s_bfe_u32 s15, s78, 0x20003
	v_pack_b32_f16 v2, v0, v61
	v_cvt_pk_f16_f32 v0, v91, v92
	v_pack_b32_f16 v66, v69, v68
	v_cvt_pk_f16_f32 v69, v63, v74
	v_cvt_pk_f16_f32 v74, v93, v82
	s_waitcnt vmcnt(10)
	v_cvt_pk_f16_f32 v78, v101, v78
	v_cvt_pk_f16_f32 v75, v75, v76
	v_pack_b32_f16 v60, v3, v0
	v_alignbit_b32 v3, v69, v61, 16
	v_alignbit_b32 v61, v74, v0, 16
	v_cvt_pk_f16_f32 v0, v67, v70
	v_alignbit_b32 v67, v78, v68, 16
	v_alignbit_b32 v68, v75, v69, 16
	v_cvt_f16_f32_e32 v69, v77
	s_add_u32 s48, s68, s48
	s_addc_u32 s49, s69, s49
	s_add_u32 s34, s31, s10
	s_addc_u32 s35, s33, s11
	v_alignbit_b32 v69, v69, v75, 16
	v_cvt_f16_f32_e32 v75, v89
	s_add_u32 s54, s48, s20
	v_cvt_pk_f16_f32 v77, v79, v80
	s_addc_u32 s55, s49, 0
	s_lshl_b32 s14, s14, 2
	v_cvt_pk_f16_f32 v83, v83, v84
	v_cvt_pk_f16_f32 v84, v71, v72
	v_alignbit_b32 v76, v77, v78, 16
	v_cvt_f16_f32_e32 v71, v85
	v_cvt_f16_f32_e32 v73, v73
	v_cvt_f16_f32_e32 v78, v81
	s_add_u32 s52, s34, s14
	v_alignbit_b32 v63, v0, v65, 16
	v_cvt_pk_f16_f32 v82, v97, v86
	v_alignbit_b32 v72, v84, v0, 16
	v_cvt_pk_f16_f32 v0, v87, v88
	s_addc_u32 s53, s35, 0
	s_lshl_b32 s80, s15, 4
	s_lshl_b32 s14, s15, 5
	v_alignbit_b32 v70, v83, v74, 16
	v_alignbit_b32 v74, v0, v82, 16
	v_alignbit_b32 v75, v75, v0, 16
	v_or_b32_e32 v0, s15, v133
	s_add_u32 s14, s54, s14
	v_cmp_eq_u32_e64 s[10:11], s15, v176
	v_cmp_eq_u32_e64 s[12:13], 0, v0
	s_addc_u32 s15, s55, 0
	v_mov_b32_e32 v0, v1
	s_waitcnt vmcnt(2)
	v_pk_add_f32 v[154:155], v[48:49], 1.0 op_sel_hi:[1,0] neg_lo:[1,0] neg_hi:[1,0]
	v_pk_add_f32 v[156:157], v[50:51], 1.0 op_sel_hi:[1,0] neg_lo:[1,0] neg_hi:[1,0]
	v_alignbit_b32 v65, v82, v90, 16
	v_pk_add_f32 v[158:159], v[44:45], 1.0 op_sel_hi:[1,0] neg_lo:[1,0] neg_hi:[1,0]
	v_alignbit_b32 v71, v71, v83, 16
	v_alignbit_b32 v73, v73, v84, 16
	v_alignbit_b32 v77, v78, v77, 16
	v_pk_add_f32 v[160:161], v[46:47], 1.0 op_sel_hi:[1,0] neg_lo:[1,0] neg_hi:[1,0]
	s_waitcnt lgkmcnt(0)
	s_barrier
	s_mov_b32 s81, -1
	s_movk_i32 s82, 0xfc00
	v_mov_b32_e32 v162, v191
	v_mov_b32_e32 v145, v169
	v_mov_b64_e32 v[166:167], v[0:1]
	v_mov_b64_e32 v[164:165], v[0:1]
	s_cmp_eq_u64 s[0:1], 0
	s_cbranch_scc1 .Lscan_init
	v_and_b32_e32 v255, 63, v130
	v_lshlrev_b32_e32 v255, 4, v255
	v_add_u32_e32 v255, 0x1d800, v255
	v_mov_b32_e32 v132, 0
	v_mov_b32_e32 v133, 0
	v_mov_b32_e32 v134, 0
	v_mov_b32_e32 v135, 0
	ds_write_b128 v255, v[132:135]
	v_and_b32_e32 v255, 8, v130
	v_mov_b32_e32 v245, 0x19000
	v_mov_b32_e32 v163, 0x18b80
	v_cmp_eq_u32_e32 vcc, 0, v255
	s_nop 1
	v_cndmask_b32_e32 v245, v245, v173, vcc
	v_cndmask_b32_e32 v163, v173, v163, vcc
	v_mov_b32_e32 v170, v183
	ds_read_b128 v[132:135], v183 offset:64
	ds_read_b128 v[136:139], v183 offset:9280
	ds_read_b128 v[164:167], v183 offset:2368
	ds_read_b128 v[184:187], v183 offset:11584
	ds_read_b128 v[188:191], v183 offset:4672
	ds_read_b128 v[192:195], v183 offset:6976
	ds_read_b128 v[196:199], v183 offset:13888
	ds_read_b128 v[246:249], v183 offset:16192
	ds_read_b128 v[250:253], v183 offset:6912
	ds_read_b128 v[140:143], v183 offset:2304
	ds_read_b128 v[154:157], v183 offset:11520
	ds_read_b128 v[158:161], v183 offset:4608
	ds_read_b128 v[176:179], v183 offset:9216
	ds_read_b128 v[180:183], v183 offset:13824
	s_waitcnt lgkmcnt(0)
	s_branch .LBB0_604

; #define LAS __attribute__((address_space(3)))
; #define SCAN_LOAD(chn) SCAN_LOAD_RAW()
; __device__ __forceinline__ void phase_scan(const Params& p, LAS unsigned char* lds) {
;     ...
;                     { unsigned m1u_ = 0xBC00BC00u; asm volatile("" : "+s"(m1u_));
;                       typedef unsigned u32x4_ __attribute__((ext_vector_type(4))); const u32x4_ m1v_ = {m1u_, m1u_, m1u_, m1u_}; const h16x8 m1_ = __builtin_bit_cast(h16x8, m1v_);
;                       const h16x8 r8 = pr + mu_r8 * (pr * m1_ + qr_), k8 = pk + mu_k8 * (pk * m1_ + qk_), v8 = pv + mu_v8 * (pv * m1_ + qv_);
;                       const h16x8 w8 = pw + mu_w8 * (pw * m1_ + qw_), a8 = pa + mu_a8 * (pa * m1_ + qa_);
;                       h16x8 tw8;
; #pragma unroll
;                       for (int pi = 0; pi < 4; ++pi) { qr[pi] = (f32x2){(float)r8[2 * pi], (float)r8[2 * pi + 1]}; qk[pi] = (f32x2){(float)k8[2 * pi], (float)k8[2 * pi + 1]};
;                           qv[2 * pi] = (float)v8[2 * pi]; qv[2 * pi + 1] = (float)v8[2 * pi + 1];
;                           const f32x2 tx = (f32x2){(float)w8[2 * pi], (float)w8[2 * pi + 1]} * 2.8853900817779268f;
;                           const f32x2 dn = (f32x2){__builtin_amdgcn_exp2f(tx[0]), __builtin_amdgcn_exp2f(tx[1])} + 1.f;
;                           const f32x2 th = (f32x2){__builtin_amdgcn_rcpf(dn[0]), __builtin_amdgcn_rcpf(dn[1])} * -2.f + 1.f;
;                           tw8[2 * pi] = (h16)th[0]; tw8[2 * pi + 1] = (h16)th[1]; }
;                       *(LAS h16x8*)(TWp + s_sub * 72 + c8) = tw8; *(LAS h16x8*)(QAp + s_sub * 72 + c8) = a8; }
;                     if (cn + 1 < SEQ / 32) SCAN_LOAD(cn + 1);
;                     LDS_WAIT();
;                     f32x4 accw[4], acca[4];
; #pragma unroll
;                     for (int ct = 0; ct < 4; ++ct) { accw[ct] = (f32x4){0.f, 0.f, 0.f, 0.f}; acca[ct] = (f32x4){0.f, 0.f, 0.f, 0.f}; }
; #pragma unroll
;                     for (int ks = 0; ks < 2; ++ks) {
;                         const h16x8 atw = *(const LAS h16x8*)(TWp + (lane & 7) * 72 + 32 * ks + 8 * (lane >> 4));
;                         const h16x8 aqa = *(const LAS h16x8*)(QAp + (lane & 7) * 72 + 32 * ks + 8 * (lane >> 4));
; #pragma unroll
;                         for (int ct = 0; ct < 4; ++ct) {
;                             const h16x8 bw = *(const LAS h16x8*)(w2T + (16 * ct + (lane & 15)) * 72 + 32 * ks + 8 * (lane >> 4));
.LBB0_609:
.LBB0_610:
	s_waitcnt lgkmcnt(0)
	v_pk_fma_f16 v222, v95, s14, v99
	v_pk_fma_f16 v218, v96, s14, v100
	v_pk_fma_f16 v219, v97, s14, v101
	ds_read_b128 v[126:129], v245 offset:18432
	ds_read_b128 v[202:205], v163 offset:19584
	ds_read_b128 v[206:209], v170
	v_pk_fma_f16 v0, v94, s14, v98
	v_pk_fma_f16 v242, v69, v219, v97
	v_pk_fma_f16 v238, v68, v218, v96
	v_pk_fma_f16 v239, v3, v222, v95
	ds_read_b128 v[230:233], v170 offset:16128
	ds_read_b128 v[234:237], v245 offset:18496
	ds_read_b128 v[226:229], v163 offset:19648
	s_waitcnt lgkmcnt(3)
	v_mfma_f32_16x16x32_f16 v[206:209], v[126:129], v[206:209], 0
	v_pk_fma_f16 v0, v2, v0, v94
	v_pk_fma_f16 v94, v86, s14, v90
	v_pk_fma_f16 v95, v87, s14, v91
	v_mfma_f32_16x16x32_f16 v[206:209], v[202:205], v[176:179], v[206:209]
	v_pk_fma_f16 v240, v61, v95, v87
	v_cvt_f32_f16_sdwa v87, v0 dst_sel:DWORD dst_unused:UNUSED_PAD src0_sel:WORD_1
	s_bitcmp1_b32 s81, 0
	v_mfma_f32_16x16x32_f16 v[214:217], v[126:129], v[140:143], 0
	s_cselect_b32 s15, 0, 0xa800
	s_add_i32 s15, s15, 0
	v_mfma_f32_16x16x32_f16 v[214:217], v[202:205], v[154:157], v[214:217]
	v_pk_fma_f16 v100, v88, s14, v92
	v_pk_fma_f16 v101, v89, s14, v93
	v_pk_fma_f16 v244, v70, v100, v88
	v_mfma_f32_16x16x32_f16 v[218:221], v[126:129], v[158:161], 0
	v_pk_fma_f16 v243, v71, v101, v89
	v_pk_fma_f16 v101, v60, v94, v86
	v_cvt_f32_f16_e32 v86, v0
	v_mfma_f32_16x16x32_f16 v[218:221], v[202:205], v[180:183], v[218:221]
	v_cvt_f32_f16_e32 v100, v101
	v_cvt_f32_f16_sdwa v101, v101 dst_sel:DWORD dst_unused:UNUSED_PAD src0_sel:WORD_1
	v_mfma_f32_16x16x32_f16 v[126:129], v[126:129], v[250:253], 0
	s_waitcnt lgkmcnt(2)
	v_mfma_f32_16x16x32_f16 v[126:129], v[202:205], v[230:233], v[126:129]
	s_waitcnt lgkmcnt(1)
	v_mfma_f32_16x16x32_f16 v[206:209], v[234:237], v[132:135], v[206:209]
	s_waitcnt lgkmcnt(0)
	v_mfma_f32_16x16x32_f16 v[206:209], v[226:229], v[136:139], v[206:209]
	v_mfma_f32_16x16x32_f16 v[214:217], v[234:237], v[164:167], v[214:217]
	v_cvt_f32_f16_e32 v88, v239
	v_cvt_f32_f16_sdwa v89, v239 dst_sel:DWORD dst_unused:UNUSED_PAD src0_sel:WORD_1
	s_nop 2
	s_nop 1
	s_waitcnt lgkmcnt(0)
	v_mfma_f32_16x16x32_f16 v[218:221], v[234:237], v[188:191], v[218:221]
	v_add_u32_e32 v255, 0x4800, v174
	v_mfma_f32_16x16x32_f16 v[214:217], v[226:229], v[184:187], v[214:217]
	v_cvt_f32_f16_e32 v94, v240
	v_cvt_f32_f16_sdwa v95, v240 dst_sel:DWORD dst_unused:UNUSED_PAD src0_sel:WORD_1
	s_waitcnt lgkmcnt(0)
	v_mfma_f32_16x16x32_f16 v[218:221], v[226:229], v[196:199], v[218:221]
	v_cvt_f32_f16_e32 v90, v238
	v_cvt_f32_f16_sdwa v91, v238 dst_sel:DWORD dst_unused:UNUSED_PAD src0_sel:WORD_1
	v_mfma_f32_16x16x32_f16 v[126:129], v[234:237], v[192:195], v[126:129]
	s_nop 0
	s_waitcnt lgkmcnt(0)
	s_waitcnt lgkmcnt(0)
	v_mfma_f32_16x16x32_f16 v[126:129], v[226:229], v[246:249], v[126:129]
	s_nop 7
	s_nop 7
	ds_write2_b32 v255, v206, v214 offset1:16
	ds_write2_b32 v255, v207, v215 offset0:64 offset1:80
	ds_write2_b32 v255, v208, v216 offset0:128 offset1:144
	ds_write2_b32 v255, v209, v217 offset0:192 offset1:208
	ds_write2_b32 v255, v218, v126 offset0:32 offset1:48
	ds_write2_b32 v255, v219, v127 offset0:96 offset1:112
	ds_write2_b32 v255, v220, v128 offset0:160 offset1:176
	ds_write2_b32 v255, v221, v129 offset0:224 offset1:240
	s_waitcnt lgkmcnt(0)
	ds_read_b128 v[126:129], v200 offset:20480
	ds_read_b128 v[206:209], v200 offset:20496
	v_pk_mul_f32 v[212:213], v[40:41], v[100:101]
	v_pk_mul_f32 v[218:219], v[42:43], v[94:95]
	ds_read_b128 v[96:99], v200 offset:18432
	ds_read_b128 v[202:205], v200 offset:18448
	s_waitcnt lgkmcnt(3)
	v_pk_add_f32 v[126:127], v[32:33], v[126:127]
	s_waitcnt lgkmcnt(2)
	v_pk_add_f32 v[208:209], v[30:31], v[208:209]
	v_pk_mul_f32 v[126:127], v[126:127], s[36:37] op_sel_hi:[1,0]
	v_cvt_f32_f16_e32 v230, v244
	v_exp_f32_e32 v126, v126
	v_exp_f32_e32 v127, v127
	v_cvt_f32_f16_sdwa v231, v244 dst_sel:DWORD dst_unused:UNUSED_PAD src0_sel:WORD_1
	v_pk_mul_f32 v[208:209], v[208:209], s[36:37] op_sel_hi:[1,0]
	v_cvt_f32_f16_e32 v210, v243
	v_pk_add_f32 v[126:127], v[126:127], 1.0 op_sel_hi:[1,0]
	v_exp_f32_e32 v208, v208
	v_rcp_f32_e32 v214, v126
	v_rcp_f32_e32 v215, v127
	v_exp_f32_e32 v209, v209
	v_cvt_f32_f16_sdwa v211, v243 dst_sel:DWORD dst_unused:UNUSED_PAD src0_sel:WORD_1
	s_waitcnt lgkmcnt(1)
	v_pk_add_f32 v[96:97], v[24:25], v[96:97]
	v_pk_add_f32 v[126:127], v[214:215], 1.0 op_sel_hi:[1,0] neg_lo:[0,1] neg_hi:[0,1]
	v_pk_fma_f32 v[126:127], v[48:49], v[126:127], 1.0 op_sel_hi:[1,1,0]
	v_pk_add_f32 v[98:99], v[26:27], v[98:99]
	v_pk_mul_f32 v[126:127], v[126:127], v[100:101]
	v_pk_add_f32 v[100:101], v[34:35], v[128:129]
	v_pk_mul_f32 v[128:129], v[126:127], v[86:87]
	v_pk_mul_f32 v[100:101], v[100:101], s[36:37] op_sel_hi:[1,0]
	v_pk_fma_f32 v[216:217], v[56:57], v[128:129], 0 op_sel_hi:[1,1,0]
	v_exp_f32_e32 v100, v100
	v_exp_f32_e32 v101, v101
	v_pk_mul_f32 v[128:129], v[218:219], v[218:219]
	v_pk_mul_f32 v[224:225], v[36:37], v[230:231]
	v_pk_fma_f32 v[220:221], v[212:213], v[212:213], v[128:129]
	v_pk_add_f32 v[100:101], v[100:101], 1.0 op_sel_hi:[1,0]
	v_pk_mul_f32 v[96:97], v[96:97], s[36:37] op_sel_hi:[1,0]
	v_rcp_f32_e32 v100, v100
	v_rcp_f32_e32 v101, v101
	v_pk_mul_f32 v[98:99], v[98:99], s[36:37] op_sel_hi:[1,0]
	v_pk_add_f32 v[208:209], v[208:209], 1.0 op_sel_hi:[1,0]
	v_exp_f32_e32 v96, v96
	v_pk_add_f32 v[128:129], v[100:101], 1.0 op_sel_hi:[1,0] neg_lo:[0,1] neg_hi:[0,1]
	v_pk_fma_f32 v[128:129], v[50:51], v[128:129], 1.0 op_sel_hi:[1,1,0]
	v_exp_f32_e32 v97, v97
	v_pk_mul_f32 v[128:129], v[128:129], v[94:95]
	v_pk_add_f32 v[94:95], v[28:29], v[206:207]
	v_pk_mul_f32 v[206:207], v[128:129], v[88:89]
	v_pk_mul_f32 v[94:95], v[94:95], s[36:37] op_sel_hi:[1,0]
	v_pk_fma_f32 v[216:217], v[58:59], v[206:207], v[216:217]
	v_exp_f32_e32 v94, v94
	v_exp_f32_e32 v95, v95
	v_exp_f32_e32 v98, v98
	v_exp_f32_e32 v99, v99
	v_pk_mul_f32 v[226:227], v[38:39], v[210:211]
	v_pk_add_f32 v[94:95], v[94:95], 1.0 op_sel_hi:[1,0]
	s_waitcnt lgkmcnt(0)
; #define LAS __attribute__((address_space(3)))
; __device__ __forceinline__ void phase_scan(const Params& p, LAS unsigned char* lds) {
;     ...
;                     for (int pi = 0; pi < 4; ++pi) {
;                         const f32x2 zw = (pi < 2 ? (f32x2){zw0[2 * pi], zw0[2 * pi + 1]} : (f32x2){zw1[2 * pi - 4], zw1[2 * pi - 3]}) + w0r[pi];
;                         const f32x2 za = (pi < 2 ? (f32x2){za0[2 * pi], za0[2 * pi + 1]} : (f32x2){za1[2 * pi - 4], za1[2 * pi - 3]}) + a0r[pi];
;                         const f32x2 tw_ = zw * -1.4426950408889634f, ta_ = za * -1.4426950408889634f;
;                         const f32x2 dw = (f32x2){__builtin_amdgcn_exp2f(tw_[0]), __builtin_amdgcn_exp2f(tw_[1])} + 1.f, da = (f32x2){__builtin_amdgcn_exp2f(ta_[0]), __builtin_amdgcn_exp2f(ta_[1])} + 1.f;
;                         const f32x2 sw = (f32x2){__builtin_amdgcn_rcpf(dw[0]), __builtin_amdgcn_rcpf(dw[1])} * -0.8750387749225136f;
;                         dec[pi] = (f32x2){__builtin_amdgcn_exp2f(sw[0]), __builtin_amdgcn_exp2f(sw[1])};
;                         av_[pi] = (f32x2){__builtin_amdgcn_rcpf(da[0]), __builtin_amdgcn_rcpf(da[1])};
;                         kk[pi] = qk[pi] * kkr[pi]; kn2 = kk[pi] * kk[pi] + kn2;
;                         kp[pi] = qk[pi] * (av_[pi] * kar[pi] + omk[pi]);
;                         sb2 = (qr[pi] * kp[pi]) * rkr[pi] + sb2; }
;                     const float kn = red8(kn2[0] + kn2[1]), sbn = red8(sb2[0] + sb2[1]);
;                     const float ninv = -rsqrtf(fmaxf(kn, 1e-12f));
;                     LAS float* dR = OPS + (cn & 1) * SET_F + s_l * 64 + c8;
; #pragma unroll
;                     for (int hf = 0; hf < 2; ++hf) {
;                         const f32x2 na0 = kk[2 * hf] * ninv, na1 = kk[2 * hf + 1] * ninv;
;                         const f32x2 nb0 = na0 * av_[2 * hf], nb1 = na1 * av_[2 * hf + 1];
;                         *(LAS f32x4*)(dR + 4 * hf) = (f32x4){qr[2 * hf][0], qr[2 * hf][1], qr[2 * hf + 1][0], qr[2 * hf + 1][1]};
;                         *(LAS f32x4*)(dR + 2048 + 4 * hf) = (f32x4){dec[2 * hf][0], dec[2 * hf][1], dec[2 * hf + 1][0], dec[2 * hf + 1][1]};
;                         *(LAS f32x4*)(dR + 4096 + 4 * hf) = (f32x4){kp[2 * hf][0], kp[2 * hf][1], kp[2 * hf + 1][0], kp[2 * hf + 1][1]};
;                         *(LAS f32x4*)(dR + 6144 + 4 * hf) = (f32x4){na0[0], na0[1], na1[0], na1[1]};
	v_pk_add_f32 v[202:203], v[20:21], v[202:203]
	v_rcp_f32_e32 v222, v94
	v_rcp_f32_e32 v223, v95
	v_pk_fma_f32 v[94:95], v[224:225], v[224:225], v[220:221]
	v_pk_add_f32 v[204:205], v[22:23], v[204:205]
	v_pk_fma_f32 v[94:95], v[226:227], v[226:227], v[94:95]
	v_pk_add_f32 v[206:207], v[222:223], 1.0 op_sel_hi:[1,0] neg_lo:[0,1] neg_hi:[0,1]
	v_pk_fma_f32 v[206:207], v[44:45], v[206:207], 1.0 op_sel_hi:[1,1,0]
	v_cvt_f32_f16_e32 v92, v242
	v_pk_mul_f32 v[206:207], v[206:207], v[230:231]
	v_cvt_f32_f16_sdwa v93, v242 dst_sel:DWORD dst_unused:UNUSED_PAD src0_sel:WORD_1
	v_pk_mul_f32 v[220:221], v[206:207], v[90:91]
	v_pk_mul_f32 v[202:203], v[202:203], s[36:37] op_sel_hi:[1,0]
	v_pk_fma_f32 v[216:217], v[52:53], v[220:221], v[216:217]
	v_rcp_f32_e32 v220, v208
	v_rcp_f32_e32 v221, v209
	v_pk_mul_f32 v[204:205], v[204:205], s[36:37] op_sel_hi:[1,0]
	v_add_f32_e32 v0, v94, v95
	v_exp_f32_e32 v202, v202
	v_exp_f32_e32 v203, v203
	v_exp_f32_e32 v204, v204
	v_exp_f32_e32 v205, v205
	v_add_f32_dpp v0, v0, v0 quad_perm:[1,0,3,2] row_mask:0xf bank_mask:0xf bound_ctrl:1
	v_pk_add_f32 v[96:97], v[96:97], 1.0 op_sel_hi:[1,0]
	v_pk_add_f32 v[98:99], v[98:99], 1.0 op_sel_hi:[1,0]
	v_pk_add_f32 v[208:209], v[220:221], 1.0 op_sel_hi:[1,0] neg_lo:[0,1] neg_hi:[0,1]
	v_pk_fma_f32 v[208:209], v[46:47], v[208:209], 1.0 op_sel_hi:[1,1,0]
	v_add_f32_dpp v0, v0, v0 quad_perm:[2,3,0,1] row_mask:0xf bank_mask:0xf bound_ctrl:1
	v_rcp_f32_e32 v96, v96
	v_rcp_f32_e32 v97, v97
	v_rcp_f32_e32 v98, v98
	v_rcp_f32_e32 v99, v99
	v_pk_mul_f32 v[208:209], v[208:209], v[210:211]
	v_add_f32_dpp v95, v0, v0 row_half_mirror row_mask:0xf bank_mask:0xf bound_ctrl:1
	v_pk_mul_f32 v[210:211], v[208:209], v[92:93]
	v_max_f32_e32 v95, 0x2b8cbccc, v95
	v_pk_add_f32 v[202:203], v[202:203], 1.0 op_sel_hi:[1,0]
	v_pk_add_f32 v[204:205], v[204:205], 1.0 op_sel_hi:[1,0]
	v_pk_fma_f32 v[210:211], v[54:55], v[210:211], v[216:217]
	v_rsq_f32_e32 v216, v95
	v_rcp_f32_e32 v202, v202
	v_rcp_f32_e32 v203, v203
	v_rcp_f32_e32 v204, v204
	v_rcp_f32_e32 v205, v205
	v_pk_mul_f32 v[96:97], v[96:97], s[38:39] op_sel_hi:[1,0]
	v_pk_mul_f32 v[98:99], v[98:99], s[38:39] op_sel_hi:[1,0]
	v_add3_u32 v95, s15, v175, v144
	v_exp_f32_e32 v96, v96
	v_exp_f32_e32 v97, v97
	v_exp_f32_e32 v98, v98
	v_exp_f32_e32 v99, v99
	v_add_u32_e32 v217, 0x8800, v95
	v_add_f32_e32 v0, v210, v211
	v_pk_mul_f32 v[210:211], v[212:213], v[216:217] op_sel_hi:[1,0] neg_lo:[0,1] neg_hi:[0,1]
	v_pk_mul_f32 v[212:213], v[218:219], v[216:217] op_sel_hi:[1,0] neg_lo:[0,1] neg_hi:[0,1]
	v_pk_mul_f32 v[202:203], v[202:203], s[38:39] op_sel_hi:[1,0]
	v_pk_mul_f32 v[204:205], v[204:205], s[38:39] op_sel_hi:[1,0]
	v_pk_mul_f32 v[100:101], v[212:213], v[100:101]
	s_waitcnt lgkmcnt(0)
	v_exp_f32_e32 v202, v202
	v_exp_f32_e32 v203, v203
	v_exp_f32_e32 v204, v204
	v_exp_f32_e32 v205, v205
	ds_write_b128 v95, v[86:89] offset:34816
	ds_write_b128 v95, v[96:99] offset:43008
	ds_write_b128 v95, v[126:129] offset:51200
	ds_write_b128 v95, v[210:213] offset:59392
	v_pk_mul_f32 v[86:87], v[210:211], v[214:215] neg_lo:[0,1] neg_hi:[0,1]
	v_xor_b32_e32 v88, 0x80000000, v100
	v_xor_b32_e32 v89, 0x80000000, v101
	v_add_f32_dpp v0, v0, v0 quad_perm:[1,0,3,2] row_mask:0xf bank_mask:0xf bound_ctrl:1
	ds_write_b128 v217, v[86:89] offset:32768
	v_pk_mul_f32 v[88:89], v[226:227], v[216:217] op_sel_hi:[1,0] neg_lo:[0,1] neg_hi:[0,1]
	v_add_f32_dpp v0, v0, v0 quad_perm:[2,3,0,1] row_mask:0xf bank_mask:0xf bound_ctrl:1
	v_mov_b32_e32 v94, 0
	v_pk_mul_f32 v[86:87], v[224:225], v[216:217] op_sel_hi:[1,0] neg_lo:[0,1] neg_hi:[0,1]
	v_pk_mul_f32 v[96:97], v[88:89], v[220:221]
	v_mov_b32_dpp v94, v0 row_half_mirror row_mask:0xf bank_mask:0xf
	ds_write_b128 v95, v[90:93] offset:34832
	ds_write_b128 v95, v[202:205] offset:43024
	ds_write_b128 v95, v[206:209] offset:51216
	ds_write_b128 v95, v[86:89] offset:59408
	v_pk_mul_f32 v[86:87], v[86:87], v[222:223] neg_lo:[0,1] neg_hi:[0,1]
	v_xor_b32_e32 v88, 0x80000000, v96
	v_xor_b32_e32 v89, 0x80000000, v97
	ds_write_b128 v217, v[86:89] offset:32784
	s_and_saveexec_b64 s[56:57], s[10:11]
	s_cbranch_execz .LBB0_612
	v_pk_fma_f16 v82, v78, s14, v82
	v_pk_fma_f16 v83, v79, s14, v83
	v_pk_fma_f16 v78, v62, v82, v78
	v_pk_fma_f16 v84, v80, s14, v84
	v_pk_fma_f16 v79, v63, v83, v79
	v_cvt_f32_f16_e32 v82, v78
	v_cvt_f32_f16_sdwa v78, v78 dst_sel:DWORD dst_unused:UNUSED_PAD src0_sel:WORD_1
	s_add_i32 s15, s15, 0x8800
	v_pk_fma_f16 v85, v81, s14, v85
	v_pk_fma_f16 v80, v72, v84, v80
	v_cvt_f32_f16_e32 v83, v79
	v_cvt_f32_f16_sdwa v79, v79 dst_sel:DWORD dst_unused:UNUSED_PAD src0_sel:WORD_1
	v_lshlrev_b32_e32 v86, 2, v169
	v_pk_fma_f16 v81, v73, v85, v81
	v_cvt_f32_f16_e32 v84, v80
	v_cvt_f32_f16_sdwa v80, v80 dst_sel:DWORD dst_unused:UNUSED_PAD src0_sel:WORD_1
	v_add3_u32 v86, s15, v201, v86
	v_cvt_f32_f16_e32 v85, v81
	v_cvt_f32_f16_sdwa v81, v81 dst_sel:DWORD dst_unused:UNUSED_PAD src0_sel:WORD_1
	v_add_u32_e32 v86, 0xa000, v86
	ds_write2_b32 v86, v82, v78 offset1:32
	ds_write2_b32 v86, v83, v79 offset0:64 offset1:96
	ds_write2_b32 v86, v84, v80 offset0:128 offset1:160
	ds_write2_b32 v86, v85, v81 offset0:192 offset1:224

; #define LAS __attribute__((address_space(3)))
; #define SCAN_LOAD(chn) SCAN_LOAD_RAW()
; __device__ __forceinline__ void phase_scan(const Params& p, LAS unsigned char* lds) {
;     ...
;                     { unsigned m1u_ = 0xBC00BC00u; asm volatile("" : "+s"(m1u_));
;                       typedef unsigned u32x4_ __attribute__((ext_vector_type(4))); const u32x4_ m1v_ = {m1u_, m1u_, m1u_, m1u_}; const h16x8 m1_ = __builtin_bit_cast(h16x8, m1v_);
;                       const h16x8 r8 = pr + mu_r8 * (pr * m1_ + qr_), k8 = pk + mu_k8 * (pk * m1_ + qk_), v8 = pv + mu_v8 * (pv * m1_ + qv_);
;                       const h16x8 w8 = pw + mu_w8 * (pw * m1_ + qw_), a8 = pa + mu_a8 * (pa * m1_ + qa_);
;                       h16x8 tw8;
; #pragma unroll
;                       for (int pi = 0; pi < 4; ++pi) { qr[pi] = (f32x2){(float)r8[2 * pi], (float)r8[2 * pi + 1]}; qk[pi] = (f32x2){(float)k8[2 * pi], (float)k8[2 * pi + 1]};
;                           qv[2 * pi] = (float)v8[2 * pi]; qv[2 * pi + 1] = (float)v8[2 * pi + 1];
;                           const f32x2 tx = (f32x2){(float)w8[2 * pi], (float)w8[2 * pi + 1]} * 2.8853900817779268f;
;                           const f32x2 dn = (f32x2){__builtin_amdgcn_exp2f(tx[0]), __builtin_amdgcn_exp2f(tx[1])} + 1.f;
;                           const f32x2 th = (f32x2){__builtin_amdgcn_rcpf(dn[0]), __builtin_amdgcn_rcpf(dn[1])} * -2.f + 1.f;
;                           tw8[2 * pi] = (h16)th[0]; tw8[2 * pi + 1] = (h16)th[1]; }
;                       *(LAS h16x8*)(TWp + s_sub * 72 + c8) = tw8; *(LAS h16x8*)(QAp + s_sub * 72 + c8) = a8; }
;                     if (cn + 1 < SEQ / 32) SCAN_LOAD(cn + 1);
;                     LDS_WAIT();
;                     f32x4 accw[4], acca[4];
; #pragma unroll
;                     for (int ct = 0; ct < 4; ++ct) { accw[ct] = (f32x4){0.f, 0.f, 0.f, 0.f}; acca[ct] = (f32x4){0.f, 0.f, 0.f, 0.f}; }
; #pragma unroll
;                     for (int ks = 0; ks < 2; ++ks) {
;                         const h16x8 atw = *(const LAS h16x8*)(TWp + (lane & 7) * 72 + 32 * ks + 8 * (lane >> 4));
;                         const h16x8 aqa = *(const LAS h16x8*)(QAp + (lane & 7) * 72 + 32 * ks + 8 * (lane >> 4));
; #pragma unroll
;                         for (int ct = 0; ct < 4; ++ct) {
;                             const h16x8 bw = *(const LAS h16x8*)(w2T + (16 * ct + (lane & 15)) * 72 + 32 * ks + 8 * (lane >> 4));
.Lpb_609:
.Lpb_610:
	s_waitcnt lgkmcnt(0)
	v_pk_fma_f16 v222, v119, s14, v123
	v_pk_fma_f16 v218, v120, s14, v124
	v_pk_fma_f16 v219, v121, s14, v125
	ds_read_b128 v[126:129], v245 offset:18432
	ds_read_b128 v[202:205], v163 offset:19584
	ds_read_b128 v[206:209], v170
	v_pk_fma_f16 v0, v118, s14, v122
	v_pk_fma_f16 v242, v69, v219, v121
	v_pk_fma_f16 v238, v68, v218, v120
	v_pk_fma_f16 v239, v3, v222, v119
	ds_read_b128 v[230:233], v170 offset:16128
	ds_read_b128 v[234:237], v245 offset:18496
	ds_read_b128 v[226:229], v163 offset:19648
	s_waitcnt lgkmcnt(3)
	v_mfma_f32_16x16x32_f16 v[206:209], v[126:129], v[206:209], 0
	v_pk_fma_f16 v0, v2, v0, v118
	v_pk_fma_f16 v118, v110, s14, v114
	v_pk_fma_f16 v119, v111, s14, v115
	v_mfma_f32_16x16x32_f16 v[206:209], v[202:205], v[176:179], v[206:209]
	v_pk_fma_f16 v240, v61, v119, v111
	v_cvt_f32_f16_sdwa v111, v0 dst_sel:DWORD dst_unused:UNUSED_PAD src0_sel:WORD_1
	s_bitcmp1_b32 s81, 0
	v_mfma_f32_16x16x32_f16 v[214:217], v[126:129], v[140:143], 0
	s_cselect_b32 s15, 0, 0xa800
	s_add_i32 s15, s15, 0
	v_mfma_f32_16x16x32_f16 v[214:217], v[202:205], v[154:157], v[214:217]
	v_pk_fma_f16 v124, v112, s14, v116
	v_pk_fma_f16 v125, v113, s14, v117
	v_pk_fma_f16 v244, v70, v124, v112
	v_mfma_f32_16x16x32_f16 v[218:221], v[126:129], v[158:161], 0
	v_pk_fma_f16 v243, v71, v125, v113
	v_pk_fma_f16 v125, v60, v118, v110
	v_cvt_f32_f16_e32 v110, v0
	v_mfma_f32_16x16x32_f16 v[218:221], v[202:205], v[180:183], v[218:221]
	v_cvt_f32_f16_e32 v124, v125
	v_cvt_f32_f16_sdwa v125, v125 dst_sel:DWORD dst_unused:UNUSED_PAD src0_sel:WORD_1
	v_mfma_f32_16x16x32_f16 v[126:129], v[126:129], v[250:253], 0
	s_waitcnt lgkmcnt(2)
	v_mfma_f32_16x16x32_f16 v[126:129], v[202:205], v[230:233], v[126:129]
	s_waitcnt lgkmcnt(1)
	v_mfma_f32_16x16x32_f16 v[206:209], v[234:237], v[132:135], v[206:209]
	s_waitcnt lgkmcnt(0)
	v_mfma_f32_16x16x32_f16 v[206:209], v[226:229], v[136:139], v[206:209]
	v_mfma_f32_16x16x32_f16 v[214:217], v[234:237], v[164:167], v[214:217]
	v_cvt_f32_f16_e32 v112, v239
	v_cvt_f32_f16_sdwa v113, v239 dst_sel:DWORD dst_unused:UNUSED_PAD src0_sel:WORD_1
	s_nop 2
	s_nop 1
	s_waitcnt lgkmcnt(0)
	v_mfma_f32_16x16x32_f16 v[218:221], v[234:237], v[188:191], v[218:221]
	v_add_u32_e32 v255, 0x4800, v174
	v_mfma_f32_16x16x32_f16 v[214:217], v[226:229], v[184:187], v[214:217]
	v_cvt_f32_f16_e32 v118, v240
	v_cvt_f32_f16_sdwa v119, v240 dst_sel:DWORD dst_unused:UNUSED_PAD src0_sel:WORD_1
	s_waitcnt lgkmcnt(0)
	v_mfma_f32_16x16x32_f16 v[218:221], v[226:229], v[196:199], v[218:221]
	v_cvt_f32_f16_e32 v114, v238
	v_cvt_f32_f16_sdwa v115, v238 dst_sel:DWORD dst_unused:UNUSED_PAD src0_sel:WORD_1
	v_mfma_f32_16x16x32_f16 v[126:129], v[234:237], v[192:195], v[126:129]
	s_nop 0
	s_waitcnt lgkmcnt(0)
	s_waitcnt lgkmcnt(0)
	v_mfma_f32_16x16x32_f16 v[126:129], v[226:229], v[246:249], v[126:129]
	s_nop 7
	s_nop 7
	ds_write2_b32 v255, v206, v214 offset1:16
	ds_write2_b32 v255, v207, v215 offset0:64 offset1:80
	ds_write2_b32 v255, v208, v216 offset0:128 offset1:144
	ds_write2_b32 v255, v209, v217 offset0:192 offset1:208
	ds_write2_b32 v255, v218, v126 offset0:32 offset1:48
	ds_write2_b32 v255, v219, v127 offset0:96 offset1:112
	ds_write2_b32 v255, v220, v128 offset0:160 offset1:176
	ds_write2_b32 v255, v221, v129 offset0:224 offset1:240
	s_waitcnt lgkmcnt(0)
	ds_read_b128 v[126:129], v200 offset:20480
	ds_read_b128 v[206:209], v200 offset:20496
	v_pk_mul_f32 v[212:213], v[40:41], v[124:125]
	v_pk_mul_f32 v[218:219], v[42:43], v[118:119]
	ds_read_b128 v[120:123], v200 offset:18432
	ds_read_b128 v[202:205], v200 offset:18448
	s_waitcnt lgkmcnt(3)
	v_pk_add_f32 v[126:127], v[32:33], v[126:127]
	s_waitcnt lgkmcnt(2)
	v_pk_add_f32 v[208:209], v[30:31], v[208:209]
	v_pk_mul_f32 v[126:127], v[126:127], s[36:37] op_sel_hi:[1,0]
	v_cvt_f32_f16_e32 v230, v244
	v_exp_f32_e32 v126, v126
	v_exp_f32_e32 v127, v127
	v_cvt_f32_f16_sdwa v231, v244 dst_sel:DWORD dst_unused:UNUSED_PAD src0_sel:WORD_1
	v_pk_mul_f32 v[208:209], v[208:209], s[36:37] op_sel_hi:[1,0]
	v_cvt_f32_f16_e32 v210, v243
	v_pk_add_f32 v[126:127], v[126:127], 1.0 op_sel_hi:[1,0]
	v_exp_f32_e32 v208, v208
	v_rcp_f32_e32 v214, v126
	v_rcp_f32_e32 v215, v127
	v_exp_f32_e32 v209, v209
	v_cvt_f32_f16_sdwa v211, v243 dst_sel:DWORD dst_unused:UNUSED_PAD src0_sel:WORD_1
	s_waitcnt lgkmcnt(1)
	v_pk_add_f32 v[120:121], v[24:25], v[120:121]
	v_pk_add_f32 v[126:127], v[214:215], 1.0 op_sel_hi:[1,0] neg_lo:[0,1] neg_hi:[0,1]
	v_pk_fma_f32 v[126:127], v[48:49], v[126:127], 1.0 op_sel_hi:[1,1,0]
	v_pk_add_f32 v[122:123], v[26:27], v[122:123]
	v_pk_mul_f32 v[126:127], v[126:127], v[124:125]
	v_pk_add_f32 v[124:125], v[34:35], v[128:129]
	v_pk_mul_f32 v[128:129], v[126:127], v[110:111]
	v_pk_mul_f32 v[124:125], v[124:125], s[36:37] op_sel_hi:[1,0]
	v_pk_fma_f32 v[216:217], v[56:57], v[128:129], 0 op_sel_hi:[1,1,0]
	v_exp_f32_e32 v124, v124
	v_exp_f32_e32 v125, v125
	v_pk_mul_f32 v[128:129], v[218:219], v[218:219]
	v_pk_mul_f32 v[224:225], v[36:37], v[230:231]
	v_pk_fma_f32 v[220:221], v[212:213], v[212:213], v[128:129]
	v_pk_add_f32 v[124:125], v[124:125], 1.0 op_sel_hi:[1,0]
	v_pk_mul_f32 v[120:121], v[120:121], s[36:37] op_sel_hi:[1,0]
	v_rcp_f32_e32 v124, v124
	v_rcp_f32_e32 v125, v125
	v_pk_mul_f32 v[122:123], v[122:123], s[36:37] op_sel_hi:[1,0]
	v_pk_add_f32 v[208:209], v[208:209], 1.0 op_sel_hi:[1,0]
	v_exp_f32_e32 v120, v120
	v_pk_add_f32 v[128:129], v[124:125], 1.0 op_sel_hi:[1,0] neg_lo:[0,1] neg_hi:[0,1]
	v_pk_fma_f32 v[128:129], v[50:51], v[128:129], 1.0 op_sel_hi:[1,1,0]
	v_exp_f32_e32 v121, v121
	v_pk_mul_f32 v[128:129], v[128:129], v[118:119]
	v_pk_add_f32 v[118:119], v[28:29], v[206:207]
	v_pk_mul_f32 v[206:207], v[128:129], v[112:113]
	v_pk_mul_f32 v[118:119], v[118:119], s[36:37] op_sel_hi:[1,0]
	v_pk_fma_f32 v[216:217], v[58:59], v[206:207], v[216:217]
	v_exp_f32_e32 v118, v118
	v_exp_f32_e32 v119, v119
	v_exp_f32_e32 v122, v122
	v_exp_f32_e32 v123, v123
	v_pk_mul_f32 v[226:227], v[38:39], v[210:211]
	v_pk_add_f32 v[118:119], v[118:119], 1.0 op_sel_hi:[1,0]
	s_waitcnt lgkmcnt(0)
; #define LAS __attribute__((address_space(3)))
; __device__ __forceinline__ void phase_scan(const Params& p, LAS unsigned char* lds) {
;     ...
;                     for (int pi = 0; pi < 4; ++pi) {
;                         const f32x2 zw = (pi < 2 ? (f32x2){zw0[2 * pi], zw0[2 * pi + 1]} : (f32x2){zw1[2 * pi - 4], zw1[2 * pi - 3]}) + w0r[pi];
;                         const f32x2 za = (pi < 2 ? (f32x2){za0[2 * pi], za0[2 * pi + 1]} : (f32x2){za1[2 * pi - 4], za1[2 * pi - 3]}) + a0r[pi];
;                         const f32x2 tw_ = zw * -1.4426950408889634f, ta_ = za * -1.4426950408889634f;
;                         const f32x2 dw = (f32x2){__builtin_amdgcn_exp2f(tw_[0]), __builtin_amdgcn_exp2f(tw_[1])} + 1.f, da = (f32x2){__builtin_amdgcn_exp2f(ta_[0]), __builtin_amdgcn_exp2f(ta_[1])} + 1.f;
;                         const f32x2 sw = (f32x2){__builtin_amdgcn_rcpf(dw[0]), __builtin_amdgcn_rcpf(dw[1])} * -0.8750387749225136f;
;                         dec[pi] = (f32x2){__builtin_amdgcn_exp2f(sw[0]), __builtin_amdgcn_exp2f(sw[1])};
;                         av_[pi] = (f32x2){__builtin_amdgcn_rcpf(da[0]), __builtin_amdgcn_rcpf(da[1])};
;                         kk[pi] = qk[pi] * kkr[pi]; kn2 = kk[pi] * kk[pi] + kn2;
;                         kp[pi] = qk[pi] * (av_[pi] * kar[pi] + omk[pi]);
;                         sb2 = (qr[pi] * kp[pi]) * rkr[pi] + sb2; }
;                     const float kn = red8(kn2[0] + kn2[1]), sbn = red8(sb2[0] + sb2[1]);
;                     const float ninv = -rsqrtf(fmaxf(kn, 1e-12f));
;                     LAS float* dR = OPS + (cn & 1) * SET_F + s_l * 64 + c8;
; #pragma unroll
;                     for (int hf = 0; hf < 2; ++hf) {
;                         const f32x2 na0 = kk[2 * hf] * ninv, na1 = kk[2 * hf + 1] * ninv;
;                         const f32x2 nb0 = na0 * av_[2 * hf], nb1 = na1 * av_[2 * hf + 1];
;                         *(LAS f32x4*)(dR + 4 * hf) = (f32x4){qr[2 * hf][0], qr[2 * hf][1], qr[2 * hf + 1][0], qr[2 * hf + 1][1]};
;                         *(LAS f32x4*)(dR + 2048 + 4 * hf) = (f32x4){dec[2 * hf][0], dec[2 * hf][1], dec[2 * hf + 1][0], dec[2 * hf + 1][1]};
;                         *(LAS f32x4*)(dR + 4096 + 4 * hf) = (f32x4){kp[2 * hf][0], kp[2 * hf][1], kp[2 * hf + 1][0], kp[2 * hf + 1][1]};
;                         *(LAS f32x4*)(dR + 6144 + 4 * hf) = (f32x4){na0[0], na0[1], na1[0], na1[1]};
	v_pk_add_f32 v[202:203], v[20:21], v[202:203]
	v_rcp_f32_e32 v222, v118
	v_rcp_f32_e32 v223, v119
	v_pk_fma_f32 v[118:119], v[224:225], v[224:225], v[220:221]
	v_pk_add_f32 v[204:205], v[22:23], v[204:205]
	v_pk_fma_f32 v[118:119], v[226:227], v[226:227], v[118:119]
	v_pk_add_f32 v[206:207], v[222:223], 1.0 op_sel_hi:[1,0] neg_lo:[0,1] neg_hi:[0,1]
	v_pk_fma_f32 v[206:207], v[44:45], v[206:207], 1.0 op_sel_hi:[1,1,0]
	v_cvt_f32_f16_e32 v116, v242
	v_pk_mul_f32 v[206:207], v[206:207], v[230:231]
	v_cvt_f32_f16_sdwa v117, v242 dst_sel:DWORD dst_unused:UNUSED_PAD src0_sel:WORD_1
	v_pk_mul_f32 v[220:221], v[206:207], v[114:115]
	v_pk_mul_f32 v[202:203], v[202:203], s[36:37] op_sel_hi:[1,0]
	v_pk_fma_f32 v[216:217], v[52:53], v[220:221], v[216:217]
	v_rcp_f32_e32 v220, v208
	v_rcp_f32_e32 v221, v209
	v_pk_mul_f32 v[204:205], v[204:205], s[36:37] op_sel_hi:[1,0]
	v_add_f32_e32 v0, v118, v119
	v_exp_f32_e32 v202, v202
	v_exp_f32_e32 v203, v203
	v_exp_f32_e32 v204, v204
	v_exp_f32_e32 v205, v205
	v_add_f32_dpp v0, v0, v0 quad_perm:[1,0,3,2] row_mask:0xf bank_mask:0xf bound_ctrl:1
	v_pk_add_f32 v[120:121], v[120:121], 1.0 op_sel_hi:[1,0]
	v_pk_add_f32 v[122:123], v[122:123], 1.0 op_sel_hi:[1,0]
	v_pk_add_f32 v[208:209], v[220:221], 1.0 op_sel_hi:[1,0] neg_lo:[0,1] neg_hi:[0,1]
	v_pk_fma_f32 v[208:209], v[46:47], v[208:209], 1.0 op_sel_hi:[1,1,0]
	v_add_f32_dpp v0, v0, v0 quad_perm:[2,3,0,1] row_mask:0xf bank_mask:0xf bound_ctrl:1
	v_rcp_f32_e32 v120, v120
	v_rcp_f32_e32 v121, v121
	v_rcp_f32_e32 v122, v122
	v_rcp_f32_e32 v123, v123
	v_pk_mul_f32 v[208:209], v[208:209], v[210:211]
	v_add_f32_dpp v119, v0, v0 row_half_mirror row_mask:0xf bank_mask:0xf bound_ctrl:1
	v_pk_mul_f32 v[210:211], v[208:209], v[116:117]
	v_max_f32_e32 v119, 0x2b8cbccc, v119
	v_pk_add_f32 v[202:203], v[202:203], 1.0 op_sel_hi:[1,0]
	v_pk_add_f32 v[204:205], v[204:205], 1.0 op_sel_hi:[1,0]
	v_pk_fma_f32 v[210:211], v[54:55], v[210:211], v[216:217]
	v_rsq_f32_e32 v216, v119
	v_rcp_f32_e32 v202, v202
	v_rcp_f32_e32 v203, v203
	v_rcp_f32_e32 v204, v204
	v_rcp_f32_e32 v205, v205
	v_pk_mul_f32 v[120:121], v[120:121], s[38:39] op_sel_hi:[1,0]
	v_pk_mul_f32 v[122:123], v[122:123], s[38:39] op_sel_hi:[1,0]
	v_add3_u32 v119, s15, v175, v144
	v_exp_f32_e32 v120, v120
	v_exp_f32_e32 v121, v121
	v_exp_f32_e32 v122, v122
	v_exp_f32_e32 v123, v123
	v_add_u32_e32 v217, 0x8800, v119
	v_add_f32_e32 v0, v210, v211
	v_pk_mul_f32 v[210:211], v[212:213], v[216:217] op_sel_hi:[1,0] neg_lo:[0,1] neg_hi:[0,1]
	v_pk_mul_f32 v[212:213], v[218:219], v[216:217] op_sel_hi:[1,0] neg_lo:[0,1] neg_hi:[0,1]
	v_pk_mul_f32 v[202:203], v[202:203], s[38:39] op_sel_hi:[1,0]
	v_pk_mul_f32 v[204:205], v[204:205], s[38:39] op_sel_hi:[1,0]
	v_pk_mul_f32 v[124:125], v[212:213], v[124:125]
	s_waitcnt lgkmcnt(0)
	v_exp_f32_e32 v202, v202
	v_exp_f32_e32 v203, v203
	v_exp_f32_e32 v204, v204
	v_exp_f32_e32 v205, v205
	ds_write_b128 v119, v[110:113] offset:34816
	ds_write_b128 v119, v[120:123] offset:43008
	ds_write_b128 v119, v[126:129] offset:51200
	ds_write_b128 v119, v[210:213] offset:59392
	v_pk_mul_f32 v[110:111], v[210:211], v[214:215] neg_lo:[0,1] neg_hi:[0,1]
	v_xor_b32_e32 v112, 0x80000000, v124
	v_xor_b32_e32 v113, 0x80000000, v125
	v_add_f32_dpp v0, v0, v0 quad_perm:[1,0,3,2] row_mask:0xf bank_mask:0xf bound_ctrl:1
	ds_write_b128 v217, v[110:113] offset:32768
	v_pk_mul_f32 v[112:113], v[226:227], v[216:217] op_sel_hi:[1,0] neg_lo:[0,1] neg_hi:[0,1]
	v_add_f32_dpp v0, v0, v0 quad_perm:[2,3,0,1] row_mask:0xf bank_mask:0xf bound_ctrl:1
	v_mov_b32_e32 v118, 0
	v_pk_mul_f32 v[110:111], v[224:225], v[216:217] op_sel_hi:[1,0] neg_lo:[0,1] neg_hi:[0,1]
	v_pk_mul_f32 v[120:121], v[112:113], v[220:221]
	v_mov_b32_dpp v118, v0 row_half_mirror row_mask:0xf bank_mask:0xf
	ds_write_b128 v119, v[114:117] offset:34832
	ds_write_b128 v119, v[202:205] offset:43024
	ds_write_b128 v119, v[206:209] offset:51216
	ds_write_b128 v119, v[110:113] offset:59408
	v_pk_mul_f32 v[110:111], v[110:111], v[222:223] neg_lo:[0,1] neg_hi:[0,1]
	v_xor_b32_e32 v112, 0x80000000, v120
	v_xor_b32_e32 v113, 0x80000000, v121
	ds_write_b128 v217, v[110:113] offset:32784
	s_and_saveexec_b64 s[56:57], s[10:11]
	s_cbranch_execz .Lpb_612
	v_pk_fma_f16 v106, v102, s14, v106
	v_pk_fma_f16 v107, v103, s14, v107
	v_pk_fma_f16 v102, v62, v106, v102
	v_pk_fma_f16 v108, v104, s14, v108
	v_pk_fma_f16 v103, v63, v107, v103
	v_cvt_f32_f16_e32 v106, v102
	v_cvt_f32_f16_sdwa v102, v102 dst_sel:DWORD dst_unused:UNUSED_PAD src0_sel:WORD_1
	s_add_i32 s15, s15, 0x8800
	v_pk_fma_f16 v109, v105, s14, v109
	v_pk_fma_f16 v104, v72, v108, v104
	v_cvt_f32_f16_e32 v107, v103
	v_cvt_f32_f16_sdwa v103, v103 dst_sel:DWORD dst_unused:UNUSED_PAD src0_sel:WORD_1
	v_lshlrev_b32_e32 v110, 2, v169
	v_pk_fma_f16 v105, v73, v109, v105
	v_cvt_f32_f16_e32 v108, v104
	v_cvt_f32_f16_sdwa v104, v104 dst_sel:DWORD dst_unused:UNUSED_PAD src0_sel:WORD_1
	v_add3_u32 v110, s15, v201, v110
	v_cvt_f32_f16_e32 v109, v105
	v_cvt_f32_f16_sdwa v105, v105 dst_sel:DWORD dst_unused:UNUSED_PAD src0_sel:WORD_1
	v_add_u32_e32 v110, 0xa000, v110
	ds_write2_b32 v110, v106, v102 offset1:32
	ds_write2_b32 v110, v107, v103 offset0:64 offset1:96
	ds_write2_b32 v110, v108, v104 offset0:128 offset1:160
	ds_write2_b32 v110, v109, v105 offset0:192 offset1:224
